# phase 1 row loop rewritten: 8 consecutive rows + 1 tail row per wave, modulation vectors summed once per wave into registers, row loads two rows ahead
# speedup vs baseline: 1.0269x; 1.0067x over previous
; __device__ __forceinline__ int get_bid() { return 2 * get_rbid() + get_hb(); }
; template <bool PART, bool SRC16 = false>
; __device__ __forceinline__ void normmod_row2(const void* __restrict__ srcv, const float* __restrict__ g, const float* __restrict__ sh, const float* __restrict__ sc, bf16_t* __restrict__ dst, int lane, const float* __restrict__ bsh = nullptr) {
;     ...
;     const f32x4 g4 = *(const f32x4*)(g + k);
;     f32x4 s4 = *(const f32x4*)(sh + k), c4 = *(const f32x4*)(sc + k);
;     if (PART) {
; #pragma unroll
;       for (int q = 1; q < 4; ++q) { s4 += *(const f32x4*)(sh + (size_t)q * 110592 + k); c4 += *(const f32x4*)(sc + (size_t)q * 110592 + k); }
;       s4 += *(const f32x4*)(bsh + k); c4 += *(const f32x4*)(bsh + 1024 + k);
;     }
;     float y[4], z[4];
; #pragma unroll
;     for (int j = 0; j < 4; ++j) { const float gm = g4[j] * (1.f + c4[j]); y[j] = (v[0][i][j] * r0) * gm + s4[j]; z[j] = (v[1][i][j] * r1) * gm + s4[j]; }
; __device__ __forceinline__ void phase_normmod_kv(CP& p) {
;     ...
;   for (int r = (get_bid() * 4 + wv) * 2; r < 18432; r += VGRID * 8) {
;     const int b = r / 2304, pp = r - b * 2304;
;     const float* src; const float* mv;
;     if (pp < 256) { src = p.ctx + ((size_t)b * 256 + pp) * 1024; mv = p.modp + (size_t)8 * 6144; }
;     else { src = p.x + ((size_t)b * 2048 + pp - 256) * 1024; mv = p.modp + (size_t)b * 6144; }
;     normmod_row2<true>(src, g, mv, mv + 1024, p.hxc + (size_t)r * 1024, lane, p.mod_b);
.LBB0_255:
	s_or_b64 exec, exec, s[6:7]
	v_readfirstlane_b32 s6, v1
	s_mov_b32 s3, s2
	s_lshr_b32 s6, s6, 8
	s_lshl_b32 s3, s3, 4
	s_lshl_b32 s6, s6, 3
	v_ashrrev_i32_e32 v2, 5, v4
	v_and_b32_e32 v2, -2, v2
	s_add_i32 s6, s6, s3
	v_add_u32_e32 v90, s6, v2
	s_mov_b64 s[6:7], exec
	s_load_dwordx2 s[4:5], s[0:1], 0x30
	s_load_dwordx2 s[8:9], s[0:1], 0x1a0
	s_load_dwordx2 s[18:19], s[0:1], 0x28
	s_load_dwordx2 s[12:13], s[0:1], 0x0
	s_load_dwordx2 s[14:15], s[0:1], 0x10
	s_load_dwordx2 s[22:23], s[0:1], 0x1d8
	v_and_b32_e32 v2, 63, v1
	v_lshlrev_b32_e32 v3, 4, v2
	v_lshlrev_b32_e32 v4, 3, v2
	v_xor_b32_e32 v6, 32, v2
	v_lshlrev_b32_e32 v6, 2, v6
	v_xor_b32_e32 v7, 16, v2
	v_lshlrev_b32_e32 v7, 2, v7
	v_xor_b32_e32 v8, 8, v2
	v_lshlrev_b32_e32 v8, 2, v8
	v_xor_b32_e32 v9, 4, v2
	v_lshlrev_b32_e32 v9, 2, v9
	v_xor_b32_e32 v10, 2, v2
	v_lshlrev_b32_e32 v10, 2, v10
	v_xor_b32_e32 v11, 1, v2
	v_lshlrev_b32_e32 v11, 2, v11
	v_add_u32_e32 v13, 0x6c000, v3
	v_add_u32_e32 v14, 0xd8000, v3
	v_add_u32_e32 v15, 0x144000, v3
	v_mov_b32_e32 v210, 0x358637bd
	v_lshrrev_b32_e32 v12, 1, v90
	s_nop 1
	v_readfirstlane_b32 s3, v12
	v_mov_b32_e32 v211, 0x3a800000
	s_lshl_b32 s10, s3, 3
	s_mul_hi_u32 s11, s10, 0x38e38e39
	s_lshr_b32 s11, s11, 9
	s_mul_i32 s16, s11, 0x900
	s_sub_u32 s16, s10, s16
	s_waitcnt lgkmcnt(0)
	s_lshl_b32 s17, s10, 11
	s_add_u32 s26, s22, s17
	s_addc_u32 s27, s23, 0
	s_add_u32 s17, s3, 0x4000
	s_lshl_b32 s17, s17, 11
	s_add_u32 s30, s22, s17
	s_addc_u32 s31, s23, 0
	s_add_u32 s17, s3, 0x3800
	s_lshl_b32 s17, s17, 12
	s_add_u32 s20, s12, s17
	s_addc_u32 s21, s13, 0
	s_cmp_lt_u32 s16, 0x100
	s_cbranch_scc1 .Lp1_ctx
	s_lshl_b32 s17, s11, 11
	s_add_u32 s17, s17, s16
	s_sub_u32 s17, s17, 0x100
	s_lshl_b32 s17, s17, 12
	s_add_u32 s24, s12, s17
	s_addc_u32 s25, s13, 0
	s_mul_i32 s17, s11, 0x6000
	s_add_u32 s28, s8, s17
	s_addc_u32 s29, s9, 0
	s_branch .Lp1_go
.Lp1_ctx:
	s_lshl_b32 s17, s11, 8
	s_add_u32 s17, s17, s16
	s_lshl_b32 s17, s17, 12
	s_add_u32 s24, s14, s17
	s_addc_u32 s25, s15, 0
	s_add_u32 s28, s8, 0x30000
	s_addc_u32 s29, s9, 0
.Lp1_go:
	s_add_u32 s10, s18, 0x1000
	s_addc_u32 s11, s19, 0
	global_load_dwordx4 v[64:67], v3, s[24:25] nt
	global_load_dwordx4 v[68:71], v3, s[24:25] offset:1024 nt
	global_load_dwordx4 v[72:75], v3, s[24:25] offset:2048 nt
	global_load_dwordx4 v[76:79], v3, s[24:25] offset:3072 nt
	s_add_u32 s24, s24, 0x1000
	s_addc_u32 s25, s25, 0
	global_load_dwordx4 v[80:83], v3, s[24:25] nt
	global_load_dwordx4 v[84:87], v3, s[24:25] offset:1024 nt
	global_load_dwordx4 v[88:91], v3, s[24:25] offset:2048 nt
	global_load_dwordx4 v[92:95], v3, s[24:25] offset:3072 nt
	s_add_u32 s24, s24, 0x1000
	s_addc_u32 s25, s25, 0
	s_add_u32 s16, s28, 0x1000
	s_addc_u32 s17, s29, 0
	global_load_dwordx4 v[112:115], v3, s[4:5]
	global_load_dwordx4 v[116:119], v3, s[18:19]
	global_load_dwordx4 v[120:123], v3, s[10:11]
	global_load_dwordx4 v[124:127], v3, s[28:29]
	global_load_dwordx4 v[128:131], v13, s[28:29]
	global_load_dwordx4 v[132:135], v14, s[28:29]
	global_load_dwordx4 v[136:139], v15, s[28:29]
	global_load_dwordx4 v[140:143], v3, s[16:17]
	global_load_dwordx4 v[144:147], v13, s[16:17]
	global_load_dwordx4 v[148:151], v14, s[16:17]
	global_load_dwordx4 v[152:155], v15, s[16:17]
	global_load_dwordx4 v[156:159], v3, s[4:5] offset:1024
	global_load_dwordx4 v[160:163], v3, s[18:19] offset:1024
	global_load_dwordx4 v[164:167], v3, s[10:11] offset:1024
	global_load_dwordx4 v[168:171], v3, s[28:29] offset:1024
	global_load_dwordx4 v[172:175], v13, s[28:29] offset:1024
	global_load_dwordx4 v[176:179], v14, s[28:29] offset:1024
	global_load_dwordx4 v[180:183], v15, s[28:29] offset:1024
	global_load_dwordx4 v[184:187], v3, s[16:17] offset:1024
	global_load_dwordx4 v[188:191], v13, s[16:17] offset:1024
	global_load_dwordx4 v[192:195], v14, s[16:17] offset:1024
	global_load_dwordx4 v[196:199], v15, s[16:17] offset:1024
	s_waitcnt vmcnt(0)
	v_pk_add_f32 v[48:49], v[124:125], v[128:129]
	v_pk_add_f32 v[48:49], v[48:49], v[132:133]
	v_pk_add_f32 v[48:49], v[48:49], v[136:137]
	v_pk_add_f32 v[32:33], v[140:141], v[144:145]
	v_pk_add_f32 v[32:33], v[32:33], v[148:149]
	v_pk_add_f32 v[32:33], v[32:33], v[152:153]
	v_pk_add_f32 v[50:51], v[126:127], v[130:131]
	v_pk_add_f32 v[50:51], v[50:51], v[134:135]
	v_pk_add_f32 v[50:51], v[50:51], v[138:139]
	v_pk_add_f32 v[34:35], v[142:143], v[146:147]
	v_pk_add_f32 v[34:35], v[34:35], v[150:151]
	v_pk_add_f32 v[34:35], v[34:35], v[154:155]
	v_add_f32_e32 v48, v116, v48
	v_add_f32_e32 v32, v120, v32
	v_add_f32_e32 v32, 1.0, v32
	v_mul_f32_e32 v32, v112, v32
	v_add_f32_e32 v49, v117, v49
	v_add_f32_e32 v33, v121, v33
	v_add_f32_e32 v33, 1.0, v33
	v_mul_f32_e32 v33, v113, v33
	v_add_f32_e32 v50, v118, v50
	v_add_f32_e32 v34, v122, v34
	v_add_f32_e32 v34, 1.0, v34
	v_mul_f32_e32 v34, v114, v34
	v_add_f32_e32 v51, v119, v51
	v_add_f32_e32 v35, v123, v35
	v_add_f32_e32 v35, 1.0, v35
	v_mul_f32_e32 v35, v115, v35
	v_pk_add_f32 v[52:53], v[168:169], v[172:173]
	v_pk_add_f32 v[52:53], v[52:53], v[176:177]
	v_pk_add_f32 v[52:53], v[52:53], v[180:181]
	v_pk_add_f32 v[36:37], v[184:185], v[188:189]
	v_pk_add_f32 v[36:37], v[36:37], v[192:193]
	v_pk_add_f32 v[36:37], v[36:37], v[196:197]
	v_pk_add_f32 v[54:55], v[170:171], v[174:175]
	v_pk_add_f32 v[54:55], v[54:55], v[178:179]
	v_pk_add_f32 v[54:55], v[54:55], v[182:183]
	v_pk_add_f32 v[38:39], v[186:187], v[190:191]
	v_pk_add_f32 v[38:39], v[38:39], v[194:195]
	v_pk_add_f32 v[38:39], v[38:39], v[198:199]
	v_add_f32_e32 v52, v160, v52
	v_add_f32_e32 v36, v164, v36
	v_add_f32_e32 v36, 1.0, v36
	v_mul_f32_e32 v36, v156, v36
	v_add_f32_e32 v53, v161, v53
; template <bool PART, bool SRC16 = false>
; __device__ __forceinline__ void normmod_row2(const void* __restrict__ srcv, const float* __restrict__ g, const float* __restrict__ sh, const float* __restrict__ sc, bf16_t* __restrict__ dst, int lane, const float* __restrict__ bsh = nullptr) {
;   f32x4 v[2][4]; float ss0 = 0.f, ss1 = 0.f;
; #pragma unroll
;   for (int i = 0; i < 4; ++i) {
;     if (SRC16) { v[0][i] = ld4_bf16((const bf16_t*)srcv + lane * 4 + 256 * i); v[1][i] = ld4_bf16((const bf16_t*)srcv + 1024 + lane * 4 + 256 * i); }
;     else { v[0][i] = __builtin_nontemporal_load((const f32x4*)((const float*)srcv + lane * 4 + 256 * i)); v[1][i] = __builtin_nontemporal_load((const f32x4*)((const float*)srcv + 1024 + lane * 4 + 256 * i)); }
;   }
; #pragma unroll
;   for (int i = 0; i < 4; ++i) {
;     ss0 += v[0][i][0] * v[0][i][0] + v[0][i][1] * v[0][i][1] + v[0][i][2] * v[0][i][2] + v[0][i][3] * v[0][i][3];
;     ss1 += v[1][i][0] * v[1][i][0] + v[1][i][1] * v[1][i][1] + v[1][i][2] * v[1][i][2] + v[1][i][3] * v[1][i][3];
;   }
;   ss0 = wave_sum(ss0); ss1 = wave_sum(ss1);
;   const float r0 = rsqrtf(ss0 * (1.0f / 1024.0f) + 1e-6f), r1 = rsqrtf(ss1 * (1.0f / 1024.0f) + 1e-6f);
; #pragma unroll
;   for (int i = 0; i < 4; ++i) {
;     const int k = lane * 4 + 256 * i;
;     const f32x4 g4 = *(const f32x4*)(g + k);
;     f32x4 s4 = *(const f32x4*)(sh + k), c4 = *(const f32x4*)(sc + k);
;     if (PART) {
; #pragma unroll
;       for (int q = 1; q < 4; ++q) { s4 += *(const f32x4*)(sh + (size_t)q * 110592 + k); c4 += *(const f32x4*)(sc + (size_t)q * 110592 + k); }
;       s4 += *(const f32x4*)(bsh + k); c4 += *(const f32x4*)(bsh + 1024 + k);
;     }
;     float y[4], z[4];
; #pragma unroll
;     for (int j = 0; j < 4; ++j) { const float gm = g4[j] * (1.f + c4[j]); y[j] = (v[0][i][j] * r0) * gm + s4[j]; z[j] = (v[1][i][j] * r1) * gm + s4[j]; }
	v_add_f32_e32 v37, v165, v37
	v_add_f32_e32 v37, 1.0, v37
	v_mul_f32_e32 v37, v157, v37
	v_add_f32_e32 v54, v162, v54
	v_add_f32_e32 v38, v166, v38
	v_add_f32_e32 v38, 1.0, v38
	v_mul_f32_e32 v38, v158, v38
	v_add_f32_e32 v55, v163, v55
	v_add_f32_e32 v39, v167, v39
	v_add_f32_e32 v39, 1.0, v39
	v_mul_f32_e32 v39, v159, v39
	global_load_dwordx4 v[112:115], v3, s[4:5] offset:2048
	global_load_dwordx4 v[116:119], v3, s[18:19] offset:2048
	global_load_dwordx4 v[120:123], v3, s[10:11] offset:2048
	global_load_dwordx4 v[124:127], v3, s[28:29] offset:2048
	global_load_dwordx4 v[128:131], v13, s[28:29] offset:2048
	global_load_dwordx4 v[132:135], v14, s[28:29] offset:2048
	global_load_dwordx4 v[136:139], v15, s[28:29] offset:2048
	global_load_dwordx4 v[140:143], v3, s[16:17] offset:2048
	global_load_dwordx4 v[144:147], v13, s[16:17] offset:2048
	global_load_dwordx4 v[148:151], v14, s[16:17] offset:2048
	global_load_dwordx4 v[152:155], v15, s[16:17] offset:2048
	global_load_dwordx4 v[156:159], v3, s[4:5] offset:3072
	global_load_dwordx4 v[160:163], v3, s[18:19] offset:3072
	global_load_dwordx4 v[164:167], v3, s[10:11] offset:3072
	global_load_dwordx4 v[168:171], v3, s[28:29] offset:3072
	global_load_dwordx4 v[172:175], v13, s[28:29] offset:3072
	global_load_dwordx4 v[176:179], v14, s[28:29] offset:3072
	global_load_dwordx4 v[180:183], v15, s[28:29] offset:3072
	global_load_dwordx4 v[184:187], v3, s[16:17] offset:3072
	global_load_dwordx4 v[188:191], v13, s[16:17] offset:3072
	global_load_dwordx4 v[192:195], v14, s[16:17] offset:3072
	global_load_dwordx4 v[196:199], v15, s[16:17] offset:3072
	s_waitcnt vmcnt(0)
	v_pk_add_f32 v[56:57], v[124:125], v[128:129]
	v_pk_add_f32 v[56:57], v[56:57], v[132:133]
	v_pk_add_f32 v[56:57], v[56:57], v[136:137]
	v_pk_add_f32 v[40:41], v[140:141], v[144:145]
	v_pk_add_f32 v[40:41], v[40:41], v[148:149]
	v_pk_add_f32 v[40:41], v[40:41], v[152:153]
	v_pk_add_f32 v[58:59], v[126:127], v[130:131]
	v_pk_add_f32 v[58:59], v[58:59], v[134:135]
	v_pk_add_f32 v[58:59], v[58:59], v[138:139]
	v_pk_add_f32 v[42:43], v[142:143], v[146:147]
	v_pk_add_f32 v[42:43], v[42:43], v[150:151]
	v_pk_add_f32 v[42:43], v[42:43], v[154:155]
	v_add_f32_e32 v56, v116, v56
	v_add_f32_e32 v40, v120, v40
	v_add_f32_e32 v40, 1.0, v40
	v_mul_f32_e32 v40, v112, v40
	v_add_f32_e32 v57, v117, v57
	v_add_f32_e32 v41, v121, v41
	v_add_f32_e32 v41, 1.0, v41
	v_mul_f32_e32 v41, v113, v41
	v_add_f32_e32 v58, v118, v58
	v_add_f32_e32 v42, v122, v42
	v_add_f32_e32 v42, 1.0, v42
	v_mul_f32_e32 v42, v114, v42
	v_add_f32_e32 v59, v119, v59
	v_add_f32_e32 v43, v123, v43
	v_add_f32_e32 v43, 1.0, v43
	v_mul_f32_e32 v43, v115, v43
	v_pk_add_f32 v[60:61], v[168:169], v[172:173]
	v_pk_add_f32 v[60:61], v[60:61], v[176:177]
	v_pk_add_f32 v[60:61], v[60:61], v[180:181]
	v_pk_add_f32 v[44:45], v[184:185], v[188:189]
	v_pk_add_f32 v[44:45], v[44:45], v[192:193]
	v_pk_add_f32 v[44:45], v[44:45], v[196:197]
	v_pk_add_f32 v[62:63], v[170:171], v[174:175]
	v_pk_add_f32 v[62:63], v[62:63], v[178:179]
	v_pk_add_f32 v[62:63], v[62:63], v[182:183]
	v_pk_add_f32 v[46:47], v[186:187], v[190:191]
	v_pk_add_f32 v[46:47], v[46:47], v[194:195]
	v_pk_add_f32 v[46:47], v[46:47], v[198:199]
	v_add_f32_e32 v60, v160, v60
	v_add_f32_e32 v44, v164, v44
	v_add_f32_e32 v44, 1.0, v44
	v_mul_f32_e32 v44, v156, v44
	v_add_f32_e32 v61, v161, v61
	v_add_f32_e32 v45, v165, v45
	v_add_f32_e32 v45, 1.0, v45
	v_mul_f32_e32 v45, v157, v45
	v_add_f32_e32 v62, v162, v62
	v_add_f32_e32 v46, v166, v46
	v_add_f32_e32 v46, 1.0, v46
	v_mul_f32_e32 v46, v158, v46
	v_add_f32_e32 v63, v163, v63
	v_add_f32_e32 v47, v167, v47
	v_add_f32_e32 v47, 1.0, v47
	v_mul_f32_e32 v47, v159, v47
	global_load_dwordx4 v[96:99], v3, s[24:25] nt
	global_load_dwordx4 v[100:103], v3, s[24:25] offset:1024 nt
	global_load_dwordx4 v[104:107], v3, s[24:25] offset:2048 nt
	global_load_dwordx4 v[108:111], v3, s[24:25] offset:3072 nt
	s_add_u32 s24, s24, 0x1000
	s_addc_u32 s25, s25, 0
	s_waitcnt vmcnt(8)
	v_mul_f32_e32 v200, v65, v65
	v_mul_f32_e32 v201, v69, v69
	v_mul_f32_e32 v202, v73, v73
	v_mul_f32_e32 v203, v77, v77
	v_fma_f32 v200, v64, v64, v200
	v_fma_f32 v201, v68, v68, v201
	v_fma_f32 v202, v72, v72, v202
	v_fma_f32 v203, v76, v76, v203
	v_fma_f32 v200, v66, v66, v200
	v_fma_f32 v201, v70, v70, v201
	v_fma_f32 v202, v74, v74, v202
	v_fma_f32 v203, v78, v78, v203
	v_fma_f32 v200, v67, v67, v200
	v_fma_f32 v201, v71, v71, v201
	v_fma_f32 v202, v75, v75, v202
	v_fma_f32 v203, v79, v79, v203
	v_add_f32_e32 v204, v200, v201
	v_add_f32_e32 v204, v204, v202
	v_add_f32_e32 v204, v204, v203
	ds_bpermute_b32 v205, v6, v204
	s_waitcnt lgkmcnt(0)
	v_add_f32_e32 v204, v204, v205
	ds_bpermute_b32 v205, v7, v204
	s_waitcnt lgkmcnt(0)
	v_add_f32_e32 v204, v204, v205
	ds_bpermute_b32 v205, v8, v204
	s_waitcnt lgkmcnt(0)
	v_add_f32_e32 v204, v204, v205
	ds_bpermute_b32 v205, v9, v204
	s_waitcnt lgkmcnt(0)
	v_add_f32_e32 v204, v204, v205
	ds_bpermute_b32 v205, v10, v204
	s_waitcnt lgkmcnt(0)
	v_add_f32_e32 v204, v204, v205
	ds_bpermute_b32 v205, v11, v204
	s_waitcnt lgkmcnt(0)
; __device__ __forceinline__ unsigned pack2(float a, float b) { unsigned r; asm("v_cvt_pk_bf16_f32 %0, %1, %2" : "=v"(r) : "v"(a), "v"(b)); return r; }
; template <bool PART, bool SRC16 = false>
; __device__ __forceinline__ void normmod_row2(const void* __restrict__ srcv, const float* __restrict__ g, const float* __restrict__ sh, const float* __restrict__ sc, bf16_t* __restrict__ dst, int lane, const float* __restrict__ bsh = nullptr) {
;     ...
;   ss0 = wave_sum(ss0); ss1 = wave_sum(ss1);
;   const float r0 = rsqrtf(ss0 * (1.0f / 1024.0f) + 1e-6f), r1 = rsqrtf(ss1 * (1.0f / 1024.0f) + 1e-6f);
; #pragma unroll
;   for (int i = 0; i < 4; ++i) {
;     const int k = lane * 4 + 256 * i;
;     const f32x4 g4 = *(const f32x4*)(g + k);
;     f32x4 s4 = *(const f32x4*)(sh + k), c4 = *(const f32x4*)(sc + k);
;     if (PART) {
; #pragma unroll
;       for (int q = 1; q < 4; ++q) { s4 += *(const f32x4*)(sh + (size_t)q * 110592 + k); c4 += *(const f32x4*)(sc + (size_t)q * 110592 + k); }
;       s4 += *(const f32x4*)(bsh + k); c4 += *(const f32x4*)(bsh + 1024 + k);
;     }
;     float y[4], z[4];
; #pragma unroll
;     for (int j = 0; j < 4; ++j) { const float gm = g4[j] * (1.f + c4[j]); y[j] = (v[0][i][j] * r0) * gm + s4[j]; z[j] = (v[1][i][j] * r1) * gm + s4[j]; }
;     uint2 u; u.x = pack2(y[0], y[1]); u.y = pack2(y[2], y[3]);
;     *(uint2*)(dst + k) = u;
;     u.x = pack2(z[0], z[1]); u.y = pack2(z[2], z[3]);
;     *(uint2*)(dst + 1024 + k) = u;
	v_add_f32_e32 v204, v204, v205
	v_fma_f32 v206, v204, v211, v210
	v_mul_f32_e32 v207, 0x4b800000, v206
	v_cmp_gt_f32_e32 vcc, 0x800000, v206
	s_nop 1
	v_cndmask_b32_e32 v207, v206, v207, vcc
	v_rsq_f32_e32 v208, v207
	s_nop 1
	v_mul_f32_e32 v207, 0x45800000, v208
	v_cndmask_b32_e32 v208, v208, v207, vcc
	v_mul_f32_e32 v64, v64, v208
	v_mul_f32_e32 v65, v65, v208
	v_mul_f32_e32 v66, v66, v208
	v_mul_f32_e32 v67, v67, v208
	v_fma_f32 v64, v64, v32, v48
	v_fma_f32 v65, v65, v33, v49
	v_fma_f32 v66, v66, v34, v50
	v_fma_f32 v67, v67, v35, v51
	v_cvt_pk_bf16_f32 v64, v64, v65
	v_cvt_pk_bf16_f32 v65, v66, v67
	s_nop 0
	global_store_dwordx2 v4, v[64:65], s[26:27]
	v_mul_f32_e32 v68, v68, v208
	v_mul_f32_e32 v69, v69, v208
	v_mul_f32_e32 v70, v70, v208
	v_mul_f32_e32 v71, v71, v208
	v_fma_f32 v68, v68, v36, v52
	v_fma_f32 v69, v69, v37, v53
	v_fma_f32 v70, v70, v38, v54
	v_fma_f32 v71, v71, v39, v55
	v_cvt_pk_bf16_f32 v68, v68, v69
	v_cvt_pk_bf16_f32 v69, v70, v71
	s_nop 0
	global_store_dwordx2 v4, v[68:69], s[26:27] offset:512
	v_mul_f32_e32 v72, v72, v208
	v_mul_f32_e32 v73, v73, v208
	v_mul_f32_e32 v74, v74, v208
	v_mul_f32_e32 v75, v75, v208
	v_fma_f32 v72, v72, v40, v56
	v_fma_f32 v73, v73, v41, v57
	v_fma_f32 v74, v74, v42, v58
	v_fma_f32 v75, v75, v43, v59
	v_cvt_pk_bf16_f32 v72, v72, v73
	v_cvt_pk_bf16_f32 v73, v74, v75
	s_nop 0
	global_store_dwordx2 v4, v[72:73], s[26:27] offset:1024
	v_mul_f32_e32 v76, v76, v208
	v_mul_f32_e32 v77, v77, v208
	v_mul_f32_e32 v78, v78, v208
	v_mul_f32_e32 v79, v79, v208
	v_fma_f32 v76, v76, v44, v60
	v_fma_f32 v77, v77, v45, v61
	v_fma_f32 v78, v78, v46, v62
	v_fma_f32 v79, v79, v47, v63
	v_cvt_pk_bf16_f32 v76, v76, v77
	v_cvt_pk_bf16_f32 v77, v78, v79
	s_nop 0
	global_store_dwordx2 v4, v[76:77], s[26:27] offset:1536
	s_add_u32 s26, s26, 0x800
	s_addc_u32 s27, s27, 0
	global_load_dwordx4 v[64:67], v3, s[24:25] nt
	global_load_dwordx4 v[68:71], v3, s[24:25] offset:1024 nt
	global_load_dwordx4 v[72:75], v3, s[24:25] offset:2048 nt
	global_load_dwordx4 v[76:79], v3, s[24:25] offset:3072 nt
	s_add_u32 s24, s24, 0x1000
	s_addc_u32 s25, s25, 0
	s_waitcnt vmcnt(12)
	v_mul_f32_e32 v200, v81, v81
	v_mul_f32_e32 v201, v85, v85
	v_mul_f32_e32 v202, v89, v89
	v_mul_f32_e32 v203, v93, v93
	v_fma_f32 v200, v80, v80, v200
	v_fma_f32 v201, v84, v84, v201
	v_fma_f32 v202, v88, v88, v202
	v_fma_f32 v203, v92, v92, v203
	v_fma_f32 v200, v82, v82, v200
	v_fma_f32 v201, v86, v86, v201
	v_fma_f32 v202, v90, v90, v202
	v_fma_f32 v203, v94, v94, v203
	v_fma_f32 v200, v83, v83, v200
	v_fma_f32 v201, v87, v87, v201
	v_fma_f32 v202, v91, v91, v202
	v_fma_f32 v203, v95, v95, v203
	v_add_f32_e32 v204, v200, v201
	v_add_f32_e32 v204, v204, v202
	v_add_f32_e32 v204, v204, v203
	ds_bpermute_b32 v205, v6, v204
	s_waitcnt lgkmcnt(0)
	v_add_f32_e32 v204, v204, v205
	ds_bpermute_b32 v205, v7, v204
	s_waitcnt lgkmcnt(0)
	v_add_f32_e32 v204, v204, v205
	ds_bpermute_b32 v205, v8, v204
	s_waitcnt lgkmcnt(0)
	v_add_f32_e32 v204, v204, v205
	ds_bpermute_b32 v205, v9, v204
	s_waitcnt lgkmcnt(0)
	v_add_f32_e32 v204, v204, v205
	ds_bpermute_b32 v205, v10, v204
	s_waitcnt lgkmcnt(0)
	v_add_f32_e32 v204, v204, v205
	ds_bpermute_b32 v205, v11, v204
	s_waitcnt lgkmcnt(0)
	v_add_f32_e32 v204, v204, v205
	v_fma_f32 v206, v204, v211, v210
	v_mul_f32_e32 v207, 0x4b800000, v206
	v_cmp_gt_f32_e32 vcc, 0x800000, v206
	s_nop 1
	v_cndmask_b32_e32 v207, v206, v207, vcc
	v_rsq_f32_e32 v208, v207
	s_nop 1
	v_mul_f32_e32 v207, 0x45800000, v208
	v_cndmask_b32_e32 v208, v208, v207, vcc
	v_mul_f32_e32 v80, v80, v208
	v_mul_f32_e32 v81, v81, v208
	v_mul_f32_e32 v82, v82, v208
	v_mul_f32_e32 v83, v83, v208
	v_fma_f32 v80, v80, v32, v48
	v_fma_f32 v81, v81, v33, v49
	v_fma_f32 v82, v82, v34, v50
	v_fma_f32 v83, v83, v35, v51
	v_cvt_pk_bf16_f32 v80, v80, v81
	v_cvt_pk_bf16_f32 v81, v82, v83
	s_nop 0
	global_store_dwordx2 v4, v[80:81], s[26:27]
	v_mul_f32_e32 v84, v84, v208
	v_mul_f32_e32 v85, v85, v208
	v_mul_f32_e32 v86, v86, v208
	v_mul_f32_e32 v87, v87, v208
	v_fma_f32 v84, v84, v36, v52
	v_fma_f32 v85, v85, v37, v53
	v_fma_f32 v86, v86, v38, v54
	v_fma_f32 v87, v87, v39, v55
	v_cvt_pk_bf16_f32 v84, v84, v85
	v_cvt_pk_bf16_f32 v85, v86, v87
	s_nop 0
	global_store_dwordx2 v4, v[84:85], s[26:27] offset:512
	v_mul_f32_e32 v88, v88, v208
	v_mul_f32_e32 v89, v89, v208
	v_mul_f32_e32 v90, v90, v208
	v_mul_f32_e32 v91, v91, v208
	v_fma_f32 v88, v88, v40, v56
	v_fma_f32 v89, v89, v41, v57
	v_fma_f32 v90, v90, v42, v58
	v_fma_f32 v91, v91, v43, v59
	v_cvt_pk_bf16_f32 v88, v88, v89
	v_cvt_pk_bf16_f32 v89, v90, v91
	s_nop 0
	global_store_dwordx2 v4, v[88:89], s[26:27] offset:1024
	v_mul_f32_e32 v92, v92, v208
	v_mul_f32_e32 v93, v93, v208
	v_mul_f32_e32 v94, v94, v208
	v_mul_f32_e32 v95, v95, v208
	v_fma_f32 v92, v92, v44, v60
	v_fma_f32 v93, v93, v45, v61
	v_fma_f32 v94, v94, v46, v62
	v_fma_f32 v95, v95, v47, v63
	v_cvt_pk_bf16_f32 v92, v92, v93
	v_cvt_pk_bf16_f32 v93, v94, v95
	s_nop 0
	global_store_dwordx2 v4, v[92:93], s[26:27] offset:1536
	s_add_u32 s26, s26, 0x800
	s_addc_u32 s27, s27, 0
	global_load_dwordx4 v[80:83], v3, s[24:25] nt
	global_load_dwordx4 v[84:87], v3, s[24:25] offset:1024 nt
	global_load_dwordx4 v[88:91], v3, s[24:25] offset:2048 nt
	global_load_dwordx4 v[92:95], v3, s[24:25] offset:3072 nt
	s_add_u32 s24, s24, 0x1000
	s_addc_u32 s25, s25, 0
	s_waitcnt vmcnt(16)
; __device__ __forceinline__ unsigned pack2(float a, float b) { unsigned r; asm("v_cvt_pk_bf16_f32 %0, %1, %2" : "=v"(r) : "v"(a), "v"(b)); return r; }
; template <bool PART, bool SRC16 = false>
; __device__ __forceinline__ void normmod_row2(const void* __restrict__ srcv, const float* __restrict__ g, const float* __restrict__ sh, const float* __restrict__ sc, bf16_t* __restrict__ dst, int lane, const float* __restrict__ bsh = nullptr) {
;   f32x4 v[2][4]; float ss0 = 0.f, ss1 = 0.f;
; #pragma unroll
;   for (int i = 0; i < 4; ++i) {
;     if (SRC16) { v[0][i] = ld4_bf16((const bf16_t*)srcv + lane * 4 + 256 * i); v[1][i] = ld4_bf16((const bf16_t*)srcv + 1024 + lane * 4 + 256 * i); }
;     else { v[0][i] = __builtin_nontemporal_load((const f32x4*)((const float*)srcv + lane * 4 + 256 * i)); v[1][i] = __builtin_nontemporal_load((const f32x4*)((const float*)srcv + 1024 + lane * 4 + 256 * i)); }
;   }
; #pragma unroll
;   for (int i = 0; i < 4; ++i) {
;     ss0 += v[0][i][0] * v[0][i][0] + v[0][i][1] * v[0][i][1] + v[0][i][2] * v[0][i][2] + v[0][i][3] * v[0][i][3];
;     ss1 += v[1][i][0] * v[1][i][0] + v[1][i][1] * v[1][i][1] + v[1][i][2] * v[1][i][2] + v[1][i][3] * v[1][i][3];
;   }
;   ss0 = wave_sum(ss0); ss1 = wave_sum(ss1);
;   const float r0 = rsqrtf(ss0 * (1.0f / 1024.0f) + 1e-6f), r1 = rsqrtf(ss1 * (1.0f / 1024.0f) + 1e-6f);
; #pragma unroll
;   for (int i = 0; i < 4; ++i) {
;     const int k = lane * 4 + 256 * i;
;     const f32x4 g4 = *(const f32x4*)(g + k);
;     f32x4 s4 = *(const f32x4*)(sh + k), c4 = *(const f32x4*)(sc + k);
;     if (PART) {
; #pragma unroll
;       for (int q = 1; q < 4; ++q) { s4 += *(const f32x4*)(sh + (size_t)q * 110592 + k); c4 += *(const f32x4*)(sc + (size_t)q * 110592 + k); }
;       s4 += *(const f32x4*)(bsh + k); c4 += *(const f32x4*)(bsh + 1024 + k);
;     }
;     float y[4], z[4];
; #pragma unroll
;     for (int j = 0; j < 4; ++j) { const float gm = g4[j] * (1.f + c4[j]); y[j] = (v[0][i][j] * r0) * gm + s4[j]; z[j] = (v[1][i][j] * r1) * gm + s4[j]; }
;     uint2 u; u.x = pack2(y[0], y[1]); u.y = pack2(y[2], y[3]);
;     *(uint2*)(dst + k) = u;
;     u.x = pack2(z[0], z[1]); u.y = pack2(z[2], z[3]);
;     *(uint2*)(dst + 1024 + k) = u;
	v_mul_f32_e32 v200, v97, v97
	v_mul_f32_e32 v201, v101, v101
	v_mul_f32_e32 v202, v105, v105
	v_mul_f32_e32 v203, v109, v109
	v_fma_f32 v200, v96, v96, v200
	v_fma_f32 v201, v100, v100, v201
	v_fma_f32 v202, v104, v104, v202
	v_fma_f32 v203, v108, v108, v203
	v_fma_f32 v200, v98, v98, v200
	v_fma_f32 v201, v102, v102, v201
	v_fma_f32 v202, v106, v106, v202
	v_fma_f32 v203, v110, v110, v203
	v_fma_f32 v200, v99, v99, v200
	v_fma_f32 v201, v103, v103, v201
	v_fma_f32 v202, v107, v107, v202
	v_fma_f32 v203, v111, v111, v203
	v_add_f32_e32 v204, v200, v201
	v_add_f32_e32 v204, v204, v202
	v_add_f32_e32 v204, v204, v203
	ds_bpermute_b32 v205, v6, v204
	s_waitcnt lgkmcnt(0)
	v_add_f32_e32 v204, v204, v205
	ds_bpermute_b32 v205, v7, v204
	s_waitcnt lgkmcnt(0)
	v_add_f32_e32 v204, v204, v205
	ds_bpermute_b32 v205, v8, v204
	s_waitcnt lgkmcnt(0)
	v_add_f32_e32 v204, v204, v205
	ds_bpermute_b32 v205, v9, v204
	s_waitcnt lgkmcnt(0)
	v_add_f32_e32 v204, v204, v205
	ds_bpermute_b32 v205, v10, v204
	s_waitcnt lgkmcnt(0)
	v_add_f32_e32 v204, v204, v205
	ds_bpermute_b32 v205, v11, v204
	s_waitcnt lgkmcnt(0)
	v_add_f32_e32 v204, v204, v205
	v_fma_f32 v206, v204, v211, v210
	v_mul_f32_e32 v207, 0x4b800000, v206
	v_cmp_gt_f32_e32 vcc, 0x800000, v206
	s_nop 1
	v_cndmask_b32_e32 v207, v206, v207, vcc
	v_rsq_f32_e32 v208, v207
	s_nop 1
	v_mul_f32_e32 v207, 0x45800000, v208
	v_cndmask_b32_e32 v208, v208, v207, vcc
	v_mul_f32_e32 v96, v96, v208
	v_mul_f32_e32 v97, v97, v208
	v_mul_f32_e32 v98, v98, v208
	v_mul_f32_e32 v99, v99, v208
	v_fma_f32 v96, v96, v32, v48
	v_fma_f32 v97, v97, v33, v49
	v_fma_f32 v98, v98, v34, v50
	v_fma_f32 v99, v99, v35, v51
	v_cvt_pk_bf16_f32 v96, v96, v97
	v_cvt_pk_bf16_f32 v97, v98, v99
	s_nop 0
	global_store_dwordx2 v4, v[96:97], s[26:27]
	v_mul_f32_e32 v100, v100, v208
	v_mul_f32_e32 v101, v101, v208
	v_mul_f32_e32 v102, v102, v208
	v_mul_f32_e32 v103, v103, v208
	v_fma_f32 v100, v100, v36, v52
	v_fma_f32 v101, v101, v37, v53
	v_fma_f32 v102, v102, v38, v54
	v_fma_f32 v103, v103, v39, v55
	v_cvt_pk_bf16_f32 v100, v100, v101
	v_cvt_pk_bf16_f32 v101, v102, v103
	s_nop 0
	global_store_dwordx2 v4, v[100:101], s[26:27] offset:512
	v_mul_f32_e32 v104, v104, v208
	v_mul_f32_e32 v105, v105, v208
	v_mul_f32_e32 v106, v106, v208
	v_mul_f32_e32 v107, v107, v208
	v_fma_f32 v104, v104, v40, v56
	v_fma_f32 v105, v105, v41, v57
	v_fma_f32 v106, v106, v42, v58
	v_fma_f32 v107, v107, v43, v59
	v_cvt_pk_bf16_f32 v104, v104, v105
	v_cvt_pk_bf16_f32 v105, v106, v107
	s_nop 0
	global_store_dwordx2 v4, v[104:105], s[26:27] offset:1024
	v_mul_f32_e32 v108, v108, v208
	v_mul_f32_e32 v109, v109, v208
	v_mul_f32_e32 v110, v110, v208
	v_mul_f32_e32 v111, v111, v208
	v_fma_f32 v108, v108, v44, v60
	v_fma_f32 v109, v109, v45, v61
	v_fma_f32 v110, v110, v46, v62
	v_fma_f32 v111, v111, v47, v63
	v_cvt_pk_bf16_f32 v108, v108, v109
	v_cvt_pk_bf16_f32 v109, v110, v111
	s_nop 0
	global_store_dwordx2 v4, v[108:109], s[26:27] offset:1536
	s_add_u32 s26, s26, 0x800
	s_addc_u32 s27, s27, 0
	global_load_dwordx4 v[96:99], v3, s[24:25] nt
	global_load_dwordx4 v[100:103], v3, s[24:25] offset:1024 nt
	global_load_dwordx4 v[104:107], v3, s[24:25] offset:2048 nt
	global_load_dwordx4 v[108:111], v3, s[24:25] offset:3072 nt
	s_add_u32 s24, s24, 0x1000
	s_addc_u32 s25, s25, 0
	s_waitcnt vmcnt(16)
	v_mul_f32_e32 v200, v65, v65
	v_mul_f32_e32 v201, v69, v69
	v_mul_f32_e32 v202, v73, v73
	v_mul_f32_e32 v203, v77, v77
	v_fma_f32 v200, v64, v64, v200
	v_fma_f32 v201, v68, v68, v201
	v_fma_f32 v202, v72, v72, v202
	v_fma_f32 v203, v76, v76, v203
	v_fma_f32 v200, v66, v66, v200
	v_fma_f32 v201, v70, v70, v201
	v_fma_f32 v202, v74, v74, v202
	v_fma_f32 v203, v78, v78, v203
	v_fma_f32 v200, v67, v67, v200
	v_fma_f32 v201, v71, v71, v201
	v_fma_f32 v202, v75, v75, v202
	v_fma_f32 v203, v79, v79, v203
	v_add_f32_e32 v204, v200, v201
	v_add_f32_e32 v204, v204, v202
	v_add_f32_e32 v204, v204, v203
	ds_bpermute_b32 v205, v6, v204
	s_waitcnt lgkmcnt(0)
	v_add_f32_e32 v204, v204, v205
	ds_bpermute_b32 v205, v7, v204
	s_waitcnt lgkmcnt(0)
	v_add_f32_e32 v204, v204, v205
	ds_bpermute_b32 v205, v8, v204
	s_waitcnt lgkmcnt(0)
	v_add_f32_e32 v204, v204, v205
	ds_bpermute_b32 v205, v9, v204
	s_waitcnt lgkmcnt(0)
	v_add_f32_e32 v204, v204, v205
	ds_bpermute_b32 v205, v10, v204
	s_waitcnt lgkmcnt(0)
	v_add_f32_e32 v204, v204, v205
	ds_bpermute_b32 v205, v11, v204
	s_waitcnt lgkmcnt(0)
	v_add_f32_e32 v204, v204, v205
	v_fma_f32 v206, v204, v211, v210
	v_mul_f32_e32 v207, 0x4b800000, v206
	v_cmp_gt_f32_e32 vcc, 0x800000, v206
	s_nop 1
	v_cndmask_b32_e32 v207, v206, v207, vcc
	v_rsq_f32_e32 v208, v207
	s_nop 1
	v_mul_f32_e32 v207, 0x45800000, v208
	v_cndmask_b32_e32 v208, v208, v207, vcc
	v_mul_f32_e32 v64, v64, v208
	v_mul_f32_e32 v65, v65, v208
	v_mul_f32_e32 v66, v66, v208
	v_mul_f32_e32 v67, v67, v208
	v_fma_f32 v64, v64, v32, v48
	v_fma_f32 v65, v65, v33, v49
	v_fma_f32 v66, v66, v34, v50
	v_fma_f32 v67, v67, v35, v51
	v_cvt_pk_bf16_f32 v64, v64, v65
	v_cvt_pk_bf16_f32 v65, v66, v67
	s_nop 0
	global_store_dwordx2 v4, v[64:65], s[26:27]
	v_mul_f32_e32 v68, v68, v208
	v_mul_f32_e32 v69, v69, v208
	v_mul_f32_e32 v70, v70, v208
	v_mul_f32_e32 v71, v71, v208
	v_fma_f32 v68, v68, v36, v52
	v_fma_f32 v69, v69, v37, v53
	v_fma_f32 v70, v70, v38, v54
	v_fma_f32 v71, v71, v39, v55
	v_cvt_pk_bf16_f32 v68, v68, v69
	v_cvt_pk_bf16_f32 v69, v70, v71
	s_nop 0
	global_store_dwordx2 v4, v[68:69], s[26:27] offset:512
	v_mul_f32_e32 v72, v72, v208
	v_mul_f32_e32 v73, v73, v208
	v_mul_f32_e32 v74, v74, v208
	v_mul_f32_e32 v75, v75, v208
	v_fma_f32 v72, v72, v40, v56
	v_fma_f32 v73, v73, v41, v57
	v_fma_f32 v74, v74, v42, v58
	v_fma_f32 v75, v75, v43, v59
	v_cvt_pk_bf16_f32 v72, v72, v73
	v_cvt_pk_bf16_f32 v73, v74, v75
	s_nop 0
	global_store_dwordx2 v4, v[72:73], s[26:27] offset:1024
	v_mul_f32_e32 v76, v76, v208
	v_mul_f32_e32 v77, v77, v208
	v_mul_f32_e32 v78, v78, v208
	v_mul_f32_e32 v79, v79, v208
	v_fma_f32 v76, v76, v44, v60
	v_fma_f32 v77, v77, v45, v61
	v_fma_f32 v78, v78, v46, v62
	v_fma_f32 v79, v79, v47, v63
	v_cvt_pk_bf16_f32 v76, v76, v77
	v_cvt_pk_bf16_f32 v77, v78, v79
	s_nop 0
	global_store_dwordx2 v4, v[76:77], s[26:27] offset:1536
	s_add_u32 s26, s26, 0x800
	s_addc_u32 s27, s27, 0
	global_load_dwordx4 v[64:67], v3, s[24:25] nt
	global_load_dwordx4 v[68:71], v3, s[24:25] offset:1024 nt
	global_load_dwordx4 v[72:75], v3, s[24:25] offset:2048 nt
	global_load_dwordx4 v[76:79], v3, s[24:25] offset:3072 nt
	s_add_u32 s24, s24, 0x1000
	s_addc_u32 s25, s25, 0
	s_waitcnt vmcnt(16)
; __device__ __forceinline__ unsigned pack2(float a, float b) { unsigned r; asm("v_cvt_pk_bf16_f32 %0, %1, %2" : "=v"(r) : "v"(a), "v"(b)); return r; }
; template <bool PART, bool SRC16 = false>
; __device__ __forceinline__ void normmod_row2(const void* __restrict__ srcv, const float* __restrict__ g, const float* __restrict__ sh, const float* __restrict__ sc, bf16_t* __restrict__ dst, int lane, const float* __restrict__ bsh = nullptr) {
;   f32x4 v[2][4]; float ss0 = 0.f, ss1 = 0.f;
; #pragma unroll
;   for (int i = 0; i < 4; ++i) {
;     if (SRC16) { v[0][i] = ld4_bf16((const bf16_t*)srcv + lane * 4 + 256 * i); v[1][i] = ld4_bf16((const bf16_t*)srcv + 1024 + lane * 4 + 256 * i); }
;     else { v[0][i] = __builtin_nontemporal_load((const f32x4*)((const float*)srcv + lane * 4 + 256 * i)); v[1][i] = __builtin_nontemporal_load((const f32x4*)((const float*)srcv + 1024 + lane * 4 + 256 * i)); }
;   }
; #pragma unroll
;   for (int i = 0; i < 4; ++i) {
;     ss0 += v[0][i][0] * v[0][i][0] + v[0][i][1] * v[0][i][1] + v[0][i][2] * v[0][i][2] + v[0][i][3] * v[0][i][3];
;     ss1 += v[1][i][0] * v[1][i][0] + v[1][i][1] * v[1][i][1] + v[1][i][2] * v[1][i][2] + v[1][i][3] * v[1][i][3];
;   }
;   ss0 = wave_sum(ss0); ss1 = wave_sum(ss1);
;   const float r0 = rsqrtf(ss0 * (1.0f / 1024.0f) + 1e-6f), r1 = rsqrtf(ss1 * (1.0f / 1024.0f) + 1e-6f);
; #pragma unroll
;   for (int i = 0; i < 4; ++i) {
;     const int k = lane * 4 + 256 * i;
;     const f32x4 g4 = *(const f32x4*)(g + k);
;     f32x4 s4 = *(const f32x4*)(sh + k), c4 = *(const f32x4*)(sc + k);
;     if (PART) {
; #pragma unroll
;       for (int q = 1; q < 4; ++q) { s4 += *(const f32x4*)(sh + (size_t)q * 110592 + k); c4 += *(const f32x4*)(sc + (size_t)q * 110592 + k); }
;       s4 += *(const f32x4*)(bsh + k); c4 += *(const f32x4*)(bsh + 1024 + k);
;     }
;     float y[4], z[4];
; #pragma unroll
;     for (int j = 0; j < 4; ++j) { const float gm = g4[j] * (1.f + c4[j]); y[j] = (v[0][i][j] * r0) * gm + s4[j]; z[j] = (v[1][i][j] * r1) * gm + s4[j]; }
;     uint2 u; u.x = pack2(y[0], y[1]); u.y = pack2(y[2], y[3]);
;     *(uint2*)(dst + k) = u;
;     u.x = pack2(z[0], z[1]); u.y = pack2(z[2], z[3]);
;     *(uint2*)(dst + 1024 + k) = u;
	v_mul_f32_e32 v200, v81, v81
	v_mul_f32_e32 v201, v85, v85
	v_mul_f32_e32 v202, v89, v89
	v_mul_f32_e32 v203, v93, v93
	v_fma_f32 v200, v80, v80, v200
	v_fma_f32 v201, v84, v84, v201
	v_fma_f32 v202, v88, v88, v202
	v_fma_f32 v203, v92, v92, v203
	v_fma_f32 v200, v82, v82, v200
	v_fma_f32 v201, v86, v86, v201
	v_fma_f32 v202, v90, v90, v202
	v_fma_f32 v203, v94, v94, v203
	v_fma_f32 v200, v83, v83, v200
	v_fma_f32 v201, v87, v87, v201
	v_fma_f32 v202, v91, v91, v202
	v_fma_f32 v203, v95, v95, v203
	v_add_f32_e32 v204, v200, v201
	v_add_f32_e32 v204, v204, v202
	v_add_f32_e32 v204, v204, v203
	ds_bpermute_b32 v205, v6, v204
	s_waitcnt lgkmcnt(0)
	v_add_f32_e32 v204, v204, v205
	ds_bpermute_b32 v205, v7, v204
	s_waitcnt lgkmcnt(0)
	v_add_f32_e32 v204, v204, v205
	ds_bpermute_b32 v205, v8, v204
	s_waitcnt lgkmcnt(0)
	v_add_f32_e32 v204, v204, v205
	ds_bpermute_b32 v205, v9, v204
	s_waitcnt lgkmcnt(0)
	v_add_f32_e32 v204, v204, v205
	ds_bpermute_b32 v205, v10, v204
	s_waitcnt lgkmcnt(0)
	v_add_f32_e32 v204, v204, v205
	ds_bpermute_b32 v205, v11, v204
	s_waitcnt lgkmcnt(0)
	v_add_f32_e32 v204, v204, v205
	v_fma_f32 v206, v204, v211, v210
	v_mul_f32_e32 v207, 0x4b800000, v206
	v_cmp_gt_f32_e32 vcc, 0x800000, v206
	s_nop 1
	v_cndmask_b32_e32 v207, v206, v207, vcc
	v_rsq_f32_e32 v208, v207
	s_nop 1
	v_mul_f32_e32 v207, 0x45800000, v208
	v_cndmask_b32_e32 v208, v208, v207, vcc
	v_mul_f32_e32 v80, v80, v208
	v_mul_f32_e32 v81, v81, v208
	v_mul_f32_e32 v82, v82, v208
	v_mul_f32_e32 v83, v83, v208
	v_fma_f32 v80, v80, v32, v48
	v_fma_f32 v81, v81, v33, v49
	v_fma_f32 v82, v82, v34, v50
	v_fma_f32 v83, v83, v35, v51
	v_cvt_pk_bf16_f32 v80, v80, v81
	v_cvt_pk_bf16_f32 v81, v82, v83
	s_nop 0
	global_store_dwordx2 v4, v[80:81], s[26:27]
	v_mul_f32_e32 v84, v84, v208
	v_mul_f32_e32 v85, v85, v208
	v_mul_f32_e32 v86, v86, v208
	v_mul_f32_e32 v87, v87, v208
	v_fma_f32 v84, v84, v36, v52
	v_fma_f32 v85, v85, v37, v53
	v_fma_f32 v86, v86, v38, v54
	v_fma_f32 v87, v87, v39, v55
	v_cvt_pk_bf16_f32 v84, v84, v85
	v_cvt_pk_bf16_f32 v85, v86, v87
	s_nop 0
	global_store_dwordx2 v4, v[84:85], s[26:27] offset:512
	v_mul_f32_e32 v88, v88, v208
	v_mul_f32_e32 v89, v89, v208
	v_mul_f32_e32 v90, v90, v208
	v_mul_f32_e32 v91, v91, v208
	v_fma_f32 v88, v88, v40, v56
	v_fma_f32 v89, v89, v41, v57
	v_fma_f32 v90, v90, v42, v58
	v_fma_f32 v91, v91, v43, v59
	v_cvt_pk_bf16_f32 v88, v88, v89
	v_cvt_pk_bf16_f32 v89, v90, v91
	s_nop 0
	global_store_dwordx2 v4, v[88:89], s[26:27] offset:1024
	v_mul_f32_e32 v92, v92, v208
	v_mul_f32_e32 v93, v93, v208
	v_mul_f32_e32 v94, v94, v208
	v_mul_f32_e32 v95, v95, v208
	v_fma_f32 v92, v92, v44, v60
	v_fma_f32 v93, v93, v45, v61
	v_fma_f32 v94, v94, v46, v62
	v_fma_f32 v95, v95, v47, v63
	v_cvt_pk_bf16_f32 v92, v92, v93
	v_cvt_pk_bf16_f32 v93, v94, v95
	s_nop 0
	global_store_dwordx2 v4, v[92:93], s[26:27] offset:1536
	s_add_u32 s26, s26, 0x800
	s_addc_u32 s27, s27, 0
	global_load_dwordx4 v[80:83], v3, s[24:25] nt
	global_load_dwordx4 v[84:87], v3, s[24:25] offset:1024 nt
	global_load_dwordx4 v[88:91], v3, s[24:25] offset:2048 nt
	global_load_dwordx4 v[92:95], v3, s[24:25] offset:3072 nt
	s_add_u32 s24, s24, 0x1000
	s_addc_u32 s25, s25, 0
	s_waitcnt vmcnt(16)
	v_mul_f32_e32 v200, v97, v97
	v_mul_f32_e32 v201, v101, v101
	v_mul_f32_e32 v202, v105, v105
	v_mul_f32_e32 v203, v109, v109
	v_fma_f32 v200, v96, v96, v200
	v_fma_f32 v201, v100, v100, v201
	v_fma_f32 v202, v104, v104, v202
	v_fma_f32 v203, v108, v108, v203
	v_fma_f32 v200, v98, v98, v200
	v_fma_f32 v201, v102, v102, v201
	v_fma_f32 v202, v106, v106, v202
	v_fma_f32 v203, v110, v110, v203
	v_fma_f32 v200, v99, v99, v200
	v_fma_f32 v201, v103, v103, v201
	v_fma_f32 v202, v107, v107, v202
	v_fma_f32 v203, v111, v111, v203
	v_add_f32_e32 v204, v200, v201
	v_add_f32_e32 v204, v204, v202
	v_add_f32_e32 v204, v204, v203
	ds_bpermute_b32 v205, v6, v204
	s_waitcnt lgkmcnt(0)
	v_add_f32_e32 v204, v204, v205
	ds_bpermute_b32 v205, v7, v204
	s_waitcnt lgkmcnt(0)
	v_add_f32_e32 v204, v204, v205
	ds_bpermute_b32 v205, v8, v204
	s_waitcnt lgkmcnt(0)
	v_add_f32_e32 v204, v204, v205
	ds_bpermute_b32 v205, v9, v204
	s_waitcnt lgkmcnt(0)
	v_add_f32_e32 v204, v204, v205
	ds_bpermute_b32 v205, v10, v204
	s_waitcnt lgkmcnt(0)
	v_add_f32_e32 v204, v204, v205
	ds_bpermute_b32 v205, v11, v204
	s_waitcnt lgkmcnt(0)
	v_add_f32_e32 v204, v204, v205
	v_fma_f32 v206, v204, v211, v210
	v_mul_f32_e32 v207, 0x4b800000, v206
	v_cmp_gt_f32_e32 vcc, 0x800000, v206
	s_nop 1
	v_cndmask_b32_e32 v207, v206, v207, vcc
	v_rsq_f32_e32 v208, v207
	s_nop 1
	v_mul_f32_e32 v207, 0x45800000, v208
	v_cndmask_b32_e32 v208, v208, v207, vcc
	v_mul_f32_e32 v96, v96, v208
	v_mul_f32_e32 v97, v97, v208
	v_mul_f32_e32 v98, v98, v208
	v_mul_f32_e32 v99, v99, v208
	v_fma_f32 v96, v96, v32, v48
	v_fma_f32 v97, v97, v33, v49
	v_fma_f32 v98, v98, v34, v50
	v_fma_f32 v99, v99, v35, v51
	v_cvt_pk_bf16_f32 v96, v96, v97
	v_cvt_pk_bf16_f32 v97, v98, v99
	s_nop 0
	global_store_dwordx2 v4, v[96:97], s[26:27]
	v_mul_f32_e32 v100, v100, v208
	v_mul_f32_e32 v101, v101, v208
	v_mul_f32_e32 v102, v102, v208
	v_mul_f32_e32 v103, v103, v208
	v_fma_f32 v100, v100, v36, v52
	v_fma_f32 v101, v101, v37, v53
	v_fma_f32 v102, v102, v38, v54
	v_fma_f32 v103, v103, v39, v55
	v_cvt_pk_bf16_f32 v100, v100, v101
	v_cvt_pk_bf16_f32 v101, v102, v103
	s_nop 0
	global_store_dwordx2 v4, v[100:101], s[26:27] offset:512
	v_mul_f32_e32 v104, v104, v208
	v_mul_f32_e32 v105, v105, v208
	v_mul_f32_e32 v106, v106, v208
	v_mul_f32_e32 v107, v107, v208
	v_fma_f32 v104, v104, v40, v56
	v_fma_f32 v105, v105, v41, v57
	v_fma_f32 v106, v106, v42, v58
	v_fma_f32 v107, v107, v43, v59
	v_cvt_pk_bf16_f32 v104, v104, v105
	v_cvt_pk_bf16_f32 v105, v106, v107
	s_nop 0
	global_store_dwordx2 v4, v[104:105], s[26:27] offset:1024
	v_mul_f32_e32 v108, v108, v208
	v_mul_f32_e32 v109, v109, v208
	v_mul_f32_e32 v110, v110, v208
	v_mul_f32_e32 v111, v111, v208
	v_fma_f32 v108, v108, v44, v60
	v_fma_f32 v109, v109, v45, v61
	v_fma_f32 v110, v110, v46, v62
	v_fma_f32 v111, v111, v47, v63
	v_cvt_pk_bf16_f32 v108, v108, v109
	v_cvt_pk_bf16_f32 v109, v110, v111
	s_nop 0
	global_store_dwordx2 v4, v[108:109], s[26:27] offset:1536
	s_add_u32 s26, s26, 0x800
	s_addc_u32 s27, s27, 0
	global_load_dwordx4 v[96:99], v3, s[20:21] nt
	global_load_dwordx4 v[100:103], v3, s[20:21] offset:1024 nt
	global_load_dwordx4 v[104:107], v3, s[20:21] offset:2048 nt
	global_load_dwordx4 v[108:111], v3, s[20:21] offset:3072 nt
	s_waitcnt vmcnt(16)
; __device__ __forceinline__ unsigned pack2(float a, float b) { unsigned r; asm("v_cvt_pk_bf16_f32 %0, %1, %2" : "=v"(r) : "v"(a), "v"(b)); return r; }
; template <bool PART, bool SRC16 = false>
; __device__ __forceinline__ void normmod_row2(const void* __restrict__ srcv, const float* __restrict__ g, const float* __restrict__ sh, const float* __restrict__ sc, bf16_t* __restrict__ dst, int lane, const float* __restrict__ bsh = nullptr) {
;   f32x4 v[2][4]; float ss0 = 0.f, ss1 = 0.f;
; #pragma unroll
;   for (int i = 0; i < 4; ++i) {
;     if (SRC16) { v[0][i] = ld4_bf16((const bf16_t*)srcv + lane * 4 + 256 * i); v[1][i] = ld4_bf16((const bf16_t*)srcv + 1024 + lane * 4 + 256 * i); }
;     else { v[0][i] = __builtin_nontemporal_load((const f32x4*)((const float*)srcv + lane * 4 + 256 * i)); v[1][i] = __builtin_nontemporal_load((const f32x4*)((const float*)srcv + 1024 + lane * 4 + 256 * i)); }
;   }
; #pragma unroll
;   for (int i = 0; i < 4; ++i) {
;     ss0 += v[0][i][0] * v[0][i][0] + v[0][i][1] * v[0][i][1] + v[0][i][2] * v[0][i][2] + v[0][i][3] * v[0][i][3];
;     ss1 += v[1][i][0] * v[1][i][0] + v[1][i][1] * v[1][i][1] + v[1][i][2] * v[1][i][2] + v[1][i][3] * v[1][i][3];
;   }
;   ss0 = wave_sum(ss0); ss1 = wave_sum(ss1);
;   const float r0 = rsqrtf(ss0 * (1.0f / 1024.0f) + 1e-6f), r1 = rsqrtf(ss1 * (1.0f / 1024.0f) + 1e-6f);
; #pragma unroll
;   for (int i = 0; i < 4; ++i) {
;     const int k = lane * 4 + 256 * i;
;     const f32x4 g4 = *(const f32x4*)(g + k);
;     f32x4 s4 = *(const f32x4*)(sh + k), c4 = *(const f32x4*)(sc + k);
;     if (PART) {
; #pragma unroll
;       for (int q = 1; q < 4; ++q) { s4 += *(const f32x4*)(sh + (size_t)q * 110592 + k); c4 += *(const f32x4*)(sc + (size_t)q * 110592 + k); }
;       s4 += *(const f32x4*)(bsh + k); c4 += *(const f32x4*)(bsh + 1024 + k);
;     }
;     float y[4], z[4];
; #pragma unroll
;     for (int j = 0; j < 4; ++j) { const float gm = g4[j] * (1.f + c4[j]); y[j] = (v[0][i][j] * r0) * gm + s4[j]; z[j] = (v[1][i][j] * r1) * gm + s4[j]; }
;     uint2 u; u.x = pack2(y[0], y[1]); u.y = pack2(y[2], y[3]);
;     *(uint2*)(dst + k) = u;
;     u.x = pack2(z[0], z[1]); u.y = pack2(z[2], z[3]);
;     *(uint2*)(dst + 1024 + k) = u;
	v_mul_f32_e32 v200, v65, v65
	v_mul_f32_e32 v201, v69, v69
	v_mul_f32_e32 v202, v73, v73
	v_mul_f32_e32 v203, v77, v77
	v_fma_f32 v200, v64, v64, v200
	v_fma_f32 v201, v68, v68, v201
	v_fma_f32 v202, v72, v72, v202
	v_fma_f32 v203, v76, v76, v203
	v_fma_f32 v200, v66, v66, v200
	v_fma_f32 v201, v70, v70, v201
	v_fma_f32 v202, v74, v74, v202
	v_fma_f32 v203, v78, v78, v203
	v_fma_f32 v200, v67, v67, v200
	v_fma_f32 v201, v71, v71, v201
	v_fma_f32 v202, v75, v75, v202
	v_fma_f32 v203, v79, v79, v203
	v_add_f32_e32 v204, v200, v201
	v_add_f32_e32 v204, v204, v202
	v_add_f32_e32 v204, v204, v203
	ds_bpermute_b32 v205, v6, v204
	s_waitcnt lgkmcnt(0)
	v_add_f32_e32 v204, v204, v205
	ds_bpermute_b32 v205, v7, v204
	s_waitcnt lgkmcnt(0)
	v_add_f32_e32 v204, v204, v205
	ds_bpermute_b32 v205, v8, v204
	s_waitcnt lgkmcnt(0)
	v_add_f32_e32 v204, v204, v205
	ds_bpermute_b32 v205, v9, v204
	s_waitcnt lgkmcnt(0)
	v_add_f32_e32 v204, v204, v205
	ds_bpermute_b32 v205, v10, v204
	s_waitcnt lgkmcnt(0)
	v_add_f32_e32 v204, v204, v205
	ds_bpermute_b32 v205, v11, v204
	s_waitcnt lgkmcnt(0)
	v_add_f32_e32 v204, v204, v205
	v_fma_f32 v206, v204, v211, v210
	v_mul_f32_e32 v207, 0x4b800000, v206
	v_cmp_gt_f32_e32 vcc, 0x800000, v206
	s_nop 1
	v_cndmask_b32_e32 v207, v206, v207, vcc
	v_rsq_f32_e32 v208, v207
	s_nop 1
	v_mul_f32_e32 v207, 0x45800000, v208
	v_cndmask_b32_e32 v208, v208, v207, vcc
	v_mul_f32_e32 v64, v64, v208
	v_mul_f32_e32 v65, v65, v208
	v_mul_f32_e32 v66, v66, v208
	v_mul_f32_e32 v67, v67, v208
	v_fma_f32 v64, v64, v32, v48
	v_fma_f32 v65, v65, v33, v49
	v_fma_f32 v66, v66, v34, v50
	v_fma_f32 v67, v67, v35, v51
	v_cvt_pk_bf16_f32 v64, v64, v65
	v_cvt_pk_bf16_f32 v65, v66, v67
	s_nop 0
	global_store_dwordx2 v4, v[64:65], s[26:27]
	v_mul_f32_e32 v68, v68, v208
	v_mul_f32_e32 v69, v69, v208
	v_mul_f32_e32 v70, v70, v208
	v_mul_f32_e32 v71, v71, v208
	v_fma_f32 v68, v68, v36, v52
	v_fma_f32 v69, v69, v37, v53
	v_fma_f32 v70, v70, v38, v54
	v_fma_f32 v71, v71, v39, v55
	v_cvt_pk_bf16_f32 v68, v68, v69
	v_cvt_pk_bf16_f32 v69, v70, v71
	s_nop 0
	global_store_dwordx2 v4, v[68:69], s[26:27] offset:512
	v_mul_f32_e32 v72, v72, v208
	v_mul_f32_e32 v73, v73, v208
	v_mul_f32_e32 v74, v74, v208
	v_mul_f32_e32 v75, v75, v208
	v_fma_f32 v72, v72, v40, v56
	v_fma_f32 v73, v73, v41, v57
	v_fma_f32 v74, v74, v42, v58
	v_fma_f32 v75, v75, v43, v59
	v_cvt_pk_bf16_f32 v72, v72, v73
	v_cvt_pk_bf16_f32 v73, v74, v75
	s_nop 0
	global_store_dwordx2 v4, v[72:73], s[26:27] offset:1024
	v_mul_f32_e32 v76, v76, v208
	v_mul_f32_e32 v77, v77, v208
	v_mul_f32_e32 v78, v78, v208
	v_mul_f32_e32 v79, v79, v208
	v_fma_f32 v76, v76, v44, v60
	v_fma_f32 v77, v77, v45, v61
	v_fma_f32 v78, v78, v46, v62
	v_fma_f32 v79, v79, v47, v63
	v_cvt_pk_bf16_f32 v76, v76, v77
	v_cvt_pk_bf16_f32 v77, v78, v79
	s_nop 0
	global_store_dwordx2 v4, v[76:77], s[26:27] offset:1536
	s_add_u32 s26, s26, 0x800
	s_addc_u32 s27, s27, 0
	s_waitcnt vmcnt(12)
	v_mul_f32_e32 v200, v81, v81
	v_mul_f32_e32 v201, v85, v85
	v_mul_f32_e32 v202, v89, v89
	v_mul_f32_e32 v203, v93, v93
	v_fma_f32 v200, v80, v80, v200
	v_fma_f32 v201, v84, v84, v201
	v_fma_f32 v202, v88, v88, v202
	v_fma_f32 v203, v92, v92, v203
	v_fma_f32 v200, v82, v82, v200
	v_fma_f32 v201, v86, v86, v201
	v_fma_f32 v202, v90, v90, v202
	v_fma_f32 v203, v94, v94, v203
	v_fma_f32 v200, v83, v83, v200
	v_fma_f32 v201, v87, v87, v201
	v_fma_f32 v202, v91, v91, v202
	v_fma_f32 v203, v95, v95, v203
	v_add_f32_e32 v204, v200, v201
	v_add_f32_e32 v204, v204, v202
	v_add_f32_e32 v204, v204, v203
	ds_bpermute_b32 v205, v6, v204
	s_waitcnt lgkmcnt(0)
	v_add_f32_e32 v204, v204, v205
	ds_bpermute_b32 v205, v7, v204
	s_waitcnt lgkmcnt(0)
	v_add_f32_e32 v204, v204, v205
	ds_bpermute_b32 v205, v8, v204
	s_waitcnt lgkmcnt(0)
	v_add_f32_e32 v204, v204, v205
	ds_bpermute_b32 v205, v9, v204
	s_waitcnt lgkmcnt(0)
	v_add_f32_e32 v204, v204, v205
	ds_bpermute_b32 v205, v10, v204
	s_waitcnt lgkmcnt(0)
	v_add_f32_e32 v204, v204, v205
	ds_bpermute_b32 v205, v11, v204
	s_waitcnt lgkmcnt(0)
	v_add_f32_e32 v204, v204, v205
	v_fma_f32 v206, v204, v211, v210
	v_mul_f32_e32 v207, 0x4b800000, v206
	v_cmp_gt_f32_e32 vcc, 0x800000, v206
	s_nop 1
	v_cndmask_b32_e32 v207, v206, v207, vcc
	v_rsq_f32_e32 v208, v207
	s_nop 1
	v_mul_f32_e32 v207, 0x45800000, v208
	v_cndmask_b32_e32 v208, v208, v207, vcc
	v_mul_f32_e32 v80, v80, v208
	v_mul_f32_e32 v81, v81, v208
	v_mul_f32_e32 v82, v82, v208
	v_mul_f32_e32 v83, v83, v208
	v_fma_f32 v80, v80, v32, v48
	v_fma_f32 v81, v81, v33, v49
	v_fma_f32 v82, v82, v34, v50
	v_fma_f32 v83, v83, v35, v51
	v_cvt_pk_bf16_f32 v80, v80, v81
	v_cvt_pk_bf16_f32 v81, v82, v83
	s_nop 0
	global_store_dwordx2 v4, v[80:81], s[26:27]
	v_mul_f32_e32 v84, v84, v208
	v_mul_f32_e32 v85, v85, v208
	v_mul_f32_e32 v86, v86, v208
	v_mul_f32_e32 v87, v87, v208
	v_fma_f32 v84, v84, v36, v52
	v_fma_f32 v85, v85, v37, v53
	v_fma_f32 v86, v86, v38, v54
	v_fma_f32 v87, v87, v39, v55
	v_cvt_pk_bf16_f32 v84, v84, v85
	v_cvt_pk_bf16_f32 v85, v86, v87
	s_nop 0
	global_store_dwordx2 v4, v[84:85], s[26:27] offset:512
	v_mul_f32_e32 v88, v88, v208
	v_mul_f32_e32 v89, v89, v208
	v_mul_f32_e32 v90, v90, v208
	v_mul_f32_e32 v91, v91, v208
	v_fma_f32 v88, v88, v40, v56
	v_fma_f32 v89, v89, v41, v57
	v_fma_f32 v90, v90, v42, v58
	v_fma_f32 v91, v91, v43, v59
	v_cvt_pk_bf16_f32 v88, v88, v89
	v_cvt_pk_bf16_f32 v89, v90, v91
	s_nop 0
	global_store_dwordx2 v4, v[88:89], s[26:27] offset:1024
	v_mul_f32_e32 v92, v92, v208
	v_mul_f32_e32 v93, v93, v208
	v_mul_f32_e32 v94, v94, v208
	v_mul_f32_e32 v95, v95, v208
	v_fma_f32 v92, v92, v44, v60
	v_fma_f32 v93, v93, v45, v61
	v_fma_f32 v94, v94, v46, v62
; __device__ __forceinline__ unsigned pack2(float a, float b) { unsigned r; asm("v_cvt_pk_bf16_f32 %0, %1, %2" : "=v"(r) : "v"(a), "v"(b)); return r; }
; template <bool PART, bool SRC16 = false>
; __device__ __forceinline__ void normmod_row2(const void* __restrict__ srcv, const float* __restrict__ g, const float* __restrict__ sh, const float* __restrict__ sc, bf16_t* __restrict__ dst, int lane, const float* __restrict__ bsh = nullptr) {
;     ...
;     const f32x4 g4 = *(const f32x4*)(g + k);
;     f32x4 s4 = *(const f32x4*)(sh + k), c4 = *(const f32x4*)(sc + k);
;     if (PART) {
; #pragma unroll
;       for (int q = 1; q < 4; ++q) { s4 += *(const f32x4*)(sh + (size_t)q * 110592 + k); c4 += *(const f32x4*)(sc + (size_t)q * 110592 + k); }
;       s4 += *(const f32x4*)(bsh + k); c4 += *(const f32x4*)(bsh + 1024 + k);
;     }
;     float y[4], z[4];
; #pragma unroll
;     for (int j = 0; j < 4; ++j) { const float gm = g4[j] * (1.f + c4[j]); y[j] = (v[0][i][j] * r0) * gm + s4[j]; z[j] = (v[1][i][j] * r1) * gm + s4[j]; }
;     uint2 u; u.x = pack2(y[0], y[1]); u.y = pack2(y[2], y[3]);
;     *(uint2*)(dst + k) = u;
;     u.x = pack2(z[0], z[1]); u.y = pack2(z[2], z[3]);
;     *(uint2*)(dst + 1024 + k) = u;
; __device__ __forceinline__ void phase_normmod_kv(CP& p) {
;     ...
;     else { src = p.x + ((size_t)b * 2048 + pp - 256) * 1024; mv = p.modp + (size_t)b * 6144; }
;     normmod_row2<true>(src, g, mv, mv + 1024, p.hxc + (size_t)r * 1024, lane, p.mod_b);
	v_fma_f32 v95, v95, v47, v63
	v_cvt_pk_bf16_f32 v92, v92, v93
	v_cvt_pk_bf16_f32 v93, v94, v95
	s_nop 0
	global_store_dwordx2 v4, v[92:93], s[26:27] offset:1536
	s_add_u32 s26, s26, 0x800
	s_addc_u32 s27, s27, 0
	s_add_u32 s28, s8, 0x2a000
	s_addc_u32 s29, s9, 0
	s_add_u32 s16, s28, 0x1000
	s_addc_u32 s17, s29, 0
	global_load_dwordx4 v[112:115], v3, s[4:5]
	global_load_dwordx4 v[116:119], v3, s[18:19]
	global_load_dwordx4 v[120:123], v3, s[10:11]
	global_load_dwordx4 v[124:127], v3, s[28:29]
	global_load_dwordx4 v[128:131], v13, s[28:29]
	global_load_dwordx4 v[132:135], v14, s[28:29]
	global_load_dwordx4 v[136:139], v15, s[28:29]
	global_load_dwordx4 v[140:143], v3, s[16:17]
	global_load_dwordx4 v[144:147], v13, s[16:17]
	global_load_dwordx4 v[148:151], v14, s[16:17]
	global_load_dwordx4 v[152:155], v15, s[16:17]
	global_load_dwordx4 v[156:159], v3, s[4:5] offset:1024
	global_load_dwordx4 v[160:163], v3, s[18:19] offset:1024
	global_load_dwordx4 v[164:167], v3, s[10:11] offset:1024
	global_load_dwordx4 v[168:171], v3, s[28:29] offset:1024
	global_load_dwordx4 v[172:175], v13, s[28:29] offset:1024
	global_load_dwordx4 v[176:179], v14, s[28:29] offset:1024
	global_load_dwordx4 v[180:183], v15, s[28:29] offset:1024
	global_load_dwordx4 v[184:187], v3, s[16:17] offset:1024
	global_load_dwordx4 v[188:191], v13, s[16:17] offset:1024
	global_load_dwordx4 v[192:195], v14, s[16:17] offset:1024
	global_load_dwordx4 v[196:199], v15, s[16:17] offset:1024
	s_waitcnt vmcnt(0)
	v_pk_add_f32 v[48:49], v[124:125], v[128:129]
	v_pk_add_f32 v[48:49], v[48:49], v[132:133]
	v_pk_add_f32 v[48:49], v[48:49], v[136:137]
	v_pk_add_f32 v[32:33], v[140:141], v[144:145]
	v_pk_add_f32 v[32:33], v[32:33], v[148:149]
	v_pk_add_f32 v[32:33], v[32:33], v[152:153]
	v_pk_add_f32 v[50:51], v[126:127], v[130:131]
	v_pk_add_f32 v[50:51], v[50:51], v[134:135]
	v_pk_add_f32 v[50:51], v[50:51], v[138:139]
	v_pk_add_f32 v[34:35], v[142:143], v[146:147]
	v_pk_add_f32 v[34:35], v[34:35], v[150:151]
	v_pk_add_f32 v[34:35], v[34:35], v[154:155]
	v_add_f32_e32 v48, v116, v48
	v_add_f32_e32 v32, v120, v32
	v_add_f32_e32 v32, 1.0, v32
	v_mul_f32_e32 v32, v112, v32
	v_add_f32_e32 v49, v117, v49
	v_add_f32_e32 v33, v121, v33
	v_add_f32_e32 v33, 1.0, v33
	v_mul_f32_e32 v33, v113, v33
	v_add_f32_e32 v50, v118, v50
	v_add_f32_e32 v34, v122, v34
	v_add_f32_e32 v34, 1.0, v34
	v_mul_f32_e32 v34, v114, v34
	v_add_f32_e32 v51, v119, v51
	v_add_f32_e32 v35, v123, v35
	v_add_f32_e32 v35, 1.0, v35
	v_mul_f32_e32 v35, v115, v35
	v_pk_add_f32 v[52:53], v[168:169], v[172:173]
	v_pk_add_f32 v[52:53], v[52:53], v[176:177]
	v_pk_add_f32 v[52:53], v[52:53], v[180:181]
	v_pk_add_f32 v[36:37], v[184:185], v[188:189]
	v_pk_add_f32 v[36:37], v[36:37], v[192:193]
	v_pk_add_f32 v[36:37], v[36:37], v[196:197]
	v_pk_add_f32 v[54:55], v[170:171], v[174:175]
	v_pk_add_f32 v[54:55], v[54:55], v[178:179]
	v_pk_add_f32 v[54:55], v[54:55], v[182:183]
	v_pk_add_f32 v[38:39], v[186:187], v[190:191]
	v_pk_add_f32 v[38:39], v[38:39], v[194:195]
	v_pk_add_f32 v[38:39], v[38:39], v[198:199]
	v_add_f32_e32 v52, v160, v52
	v_add_f32_e32 v36, v164, v36
	v_add_f32_e32 v36, 1.0, v36
	v_mul_f32_e32 v36, v156, v36
	v_add_f32_e32 v53, v161, v53
	v_add_f32_e32 v37, v165, v37
	v_add_f32_e32 v37, 1.0, v37
	v_mul_f32_e32 v37, v157, v37
	v_add_f32_e32 v54, v162, v54
	v_add_f32_e32 v38, v166, v38
	v_add_f32_e32 v38, 1.0, v38
	v_mul_f32_e32 v38, v158, v38
	v_add_f32_e32 v55, v163, v55
	v_add_f32_e32 v39, v167, v39
	v_add_f32_e32 v39, 1.0, v39
	v_mul_f32_e32 v39, v159, v39
	global_load_dwordx4 v[112:115], v3, s[4:5] offset:2048
	global_load_dwordx4 v[116:119], v3, s[18:19] offset:2048
	global_load_dwordx4 v[120:123], v3, s[10:11] offset:2048
	global_load_dwordx4 v[124:127], v3, s[28:29] offset:2048
	global_load_dwordx4 v[128:131], v13, s[28:29] offset:2048
	global_load_dwordx4 v[132:135], v14, s[28:29] offset:2048
	global_load_dwordx4 v[136:139], v15, s[28:29] offset:2048
	global_load_dwordx4 v[140:143], v3, s[16:17] offset:2048
	global_load_dwordx4 v[144:147], v13, s[16:17] offset:2048
	global_load_dwordx4 v[148:151], v14, s[16:17] offset:2048
	global_load_dwordx4 v[152:155], v15, s[16:17] offset:2048
	global_load_dwordx4 v[156:159], v3, s[4:5] offset:3072
	global_load_dwordx4 v[160:163], v3, s[18:19] offset:3072
	global_load_dwordx4 v[164:167], v3, s[10:11] offset:3072
	global_load_dwordx4 v[168:171], v3, s[28:29] offset:3072
	global_load_dwordx4 v[172:175], v13, s[28:29] offset:3072
	global_load_dwordx4 v[176:179], v14, s[28:29] offset:3072
	global_load_dwordx4 v[180:183], v15, s[28:29] offset:3072
	global_load_dwordx4 v[184:187], v3, s[16:17] offset:3072
	global_load_dwordx4 v[188:191], v13, s[16:17] offset:3072
	global_load_dwordx4 v[192:195], v14, s[16:17] offset:3072
	global_load_dwordx4 v[196:199], v15, s[16:17] offset:3072
	s_waitcnt vmcnt(0)
; template <bool PART, bool SRC16 = false>
; __device__ __forceinline__ void normmod_row2(const void* __restrict__ srcv, const float* __restrict__ g, const float* __restrict__ sh, const float* __restrict__ sc, bf16_t* __restrict__ dst, int lane, const float* __restrict__ bsh = nullptr) {
;   f32x4 v[2][4]; float ss0 = 0.f, ss1 = 0.f;
; #pragma unroll
;   for (int i = 0; i < 4; ++i) {
;     if (SRC16) { v[0][i] = ld4_bf16((const bf16_t*)srcv + lane * 4 + 256 * i); v[1][i] = ld4_bf16((const bf16_t*)srcv + 1024 + lane * 4 + 256 * i); }
;     else { v[0][i] = __builtin_nontemporal_load((const f32x4*)((const float*)srcv + lane * 4 + 256 * i)); v[1][i] = __builtin_nontemporal_load((const f32x4*)((const float*)srcv + 1024 + lane * 4 + 256 * i)); }
;   }
; #pragma unroll
;   for (int i = 0; i < 4; ++i) {
;     ss0 += v[0][i][0] * v[0][i][0] + v[0][i][1] * v[0][i][1] + v[0][i][2] * v[0][i][2] + v[0][i][3] * v[0][i][3];
;     ss1 += v[1][i][0] * v[1][i][0] + v[1][i][1] * v[1][i][1] + v[1][i][2] * v[1][i][2] + v[1][i][3] * v[1][i][3];
;   }
;   ss0 = wave_sum(ss0); ss1 = wave_sum(ss1);
;   const float r0 = rsqrtf(ss0 * (1.0f / 1024.0f) + 1e-6f), r1 = rsqrtf(ss1 * (1.0f / 1024.0f) + 1e-6f);
; #pragma unroll
;   for (int i = 0; i < 4; ++i) {
;     const int k = lane * 4 + 256 * i;
;     const f32x4 g4 = *(const f32x4*)(g + k);
;     f32x4 s4 = *(const f32x4*)(sh + k), c4 = *(const f32x4*)(sc + k);
;     if (PART) {
; #pragma unroll
;       for (int q = 1; q < 4; ++q) { s4 += *(const f32x4*)(sh + (size_t)q * 110592 + k); c4 += *(const f32x4*)(sc + (size_t)q * 110592 + k); }
;       s4 += *(const f32x4*)(bsh + k); c4 += *(const f32x4*)(bsh + 1024 + k);
;     }
;     float y[4], z[4];
; #pragma unroll
;     for (int j = 0; j < 4; ++j) { const float gm = g4[j] * (1.f + c4[j]); y[j] = (v[0][i][j] * r0) * gm + s4[j]; z[j] = (v[1][i][j] * r1) * gm + s4[j]; }
;     uint2 u; u.x = pack2(y[0], y[1]); u.y = pack2(y[2], y[3]);
;     *(uint2*)(dst + k) = u;
;     u.x = pack2(z[0], z[1]); u.y = pack2(z[2], z[3]);
;     *(uint2*)(dst + 1024 + k) = u;
;   }
; }
; __device__ __forceinline__ void phase_normmod_kv(CP& p) {
;     ...
;   for (int r = (get_bid() * 4 + wv) * 2; r < 18432; r += VGRID * 8) {
;     const int b = r / 2304, pp = r - b * 2304;
;     const float* src; const float* mv;
;     if (pp < 256) { src = p.ctx + ((size_t)b * 256 + pp) * 1024; mv = p.modp + (size_t)8 * 6144; }
	v_pk_add_f32 v[56:57], v[124:125], v[128:129]
	v_pk_add_f32 v[56:57], v[56:57], v[132:133]
	v_pk_add_f32 v[56:57], v[56:57], v[136:137]
	v_pk_add_f32 v[40:41], v[140:141], v[144:145]
	v_pk_add_f32 v[40:41], v[40:41], v[148:149]
	v_pk_add_f32 v[40:41], v[40:41], v[152:153]
	v_pk_add_f32 v[58:59], v[126:127], v[130:131]
	v_pk_add_f32 v[58:59], v[58:59], v[134:135]
	v_pk_add_f32 v[58:59], v[58:59], v[138:139]
	v_pk_add_f32 v[42:43], v[142:143], v[146:147]
	v_pk_add_f32 v[42:43], v[42:43], v[150:151]
	v_pk_add_f32 v[42:43], v[42:43], v[154:155]
	v_add_f32_e32 v56, v116, v56
	v_add_f32_e32 v40, v120, v40
	v_add_f32_e32 v40, 1.0, v40
	v_mul_f32_e32 v40, v112, v40
	v_add_f32_e32 v57, v117, v57
	v_add_f32_e32 v41, v121, v41
	v_add_f32_e32 v41, 1.0, v41
	v_mul_f32_e32 v41, v113, v41
	v_add_f32_e32 v58, v118, v58
	v_add_f32_e32 v42, v122, v42
	v_add_f32_e32 v42, 1.0, v42
	v_mul_f32_e32 v42, v114, v42
	v_add_f32_e32 v59, v119, v59
	v_add_f32_e32 v43, v123, v43
	v_add_f32_e32 v43, 1.0, v43
	v_mul_f32_e32 v43, v115, v43
	v_pk_add_f32 v[60:61], v[168:169], v[172:173]
	v_pk_add_f32 v[60:61], v[60:61], v[176:177]
	v_pk_add_f32 v[60:61], v[60:61], v[180:181]
	v_pk_add_f32 v[44:45], v[184:185], v[188:189]
	v_pk_add_f32 v[44:45], v[44:45], v[192:193]
	v_pk_add_f32 v[44:45], v[44:45], v[196:197]
	v_pk_add_f32 v[62:63], v[170:171], v[174:175]
	v_pk_add_f32 v[62:63], v[62:63], v[178:179]
	v_pk_add_f32 v[62:63], v[62:63], v[182:183]
	v_pk_add_f32 v[46:47], v[186:187], v[190:191]
	v_pk_add_f32 v[46:47], v[46:47], v[194:195]
	v_pk_add_f32 v[46:47], v[46:47], v[198:199]
	v_add_f32_e32 v60, v160, v60
	v_add_f32_e32 v44, v164, v44
	v_add_f32_e32 v44, 1.0, v44
	v_mul_f32_e32 v44, v156, v44
	v_add_f32_e32 v61, v161, v61
	v_add_f32_e32 v45, v165, v45
	v_add_f32_e32 v45, 1.0, v45
	v_mul_f32_e32 v45, v157, v45
	v_add_f32_e32 v62, v162, v62
	v_add_f32_e32 v46, v166, v46
	v_add_f32_e32 v46, 1.0, v46
	v_mul_f32_e32 v46, v158, v46
	v_add_f32_e32 v63, v163, v63
	v_add_f32_e32 v47, v167, v47
	v_add_f32_e32 v47, 1.0, v47
	v_mul_f32_e32 v47, v159, v47
	v_mul_f32_e32 v200, v97, v97
	v_mul_f32_e32 v201, v101, v101
	v_mul_f32_e32 v202, v105, v105
	v_mul_f32_e32 v203, v109, v109
	v_fma_f32 v200, v96, v96, v200
	v_fma_f32 v201, v100, v100, v201
	v_fma_f32 v202, v104, v104, v202
	v_fma_f32 v203, v108, v108, v203
	v_fma_f32 v200, v98, v98, v200
	v_fma_f32 v201, v102, v102, v201
	v_fma_f32 v202, v106, v106, v202
	v_fma_f32 v203, v110, v110, v203
	v_fma_f32 v200, v99, v99, v200
	v_fma_f32 v201, v103, v103, v201
	v_fma_f32 v202, v107, v107, v202
	v_fma_f32 v203, v111, v111, v203
	v_add_f32_e32 v204, v200, v201
	v_add_f32_e32 v204, v204, v202
	v_add_f32_e32 v204, v204, v203
	ds_bpermute_b32 v205, v6, v204
	s_waitcnt lgkmcnt(0)
	v_add_f32_e32 v204, v204, v205
	ds_bpermute_b32 v205, v7, v204
	s_waitcnt lgkmcnt(0)
	v_add_f32_e32 v204, v204, v205
	ds_bpermute_b32 v205, v8, v204
	s_waitcnt lgkmcnt(0)
	v_add_f32_e32 v204, v204, v205
	ds_bpermute_b32 v205, v9, v204
	s_waitcnt lgkmcnt(0)
	v_add_f32_e32 v204, v204, v205
	ds_bpermute_b32 v205, v10, v204
	s_waitcnt lgkmcnt(0)
	v_add_f32_e32 v204, v204, v205
	ds_bpermute_b32 v205, v11, v204
	s_waitcnt lgkmcnt(0)
	v_add_f32_e32 v204, v204, v205
	v_fma_f32 v206, v204, v211, v210
	v_mul_f32_e32 v207, 0x4b800000, v206
	v_cmp_gt_f32_e32 vcc, 0x800000, v206
	s_nop 1
	v_cndmask_b32_e32 v207, v206, v207, vcc
	v_rsq_f32_e32 v208, v207
	s_nop 1
	v_mul_f32_e32 v207, 0x45800000, v208
	v_cndmask_b32_e32 v208, v208, v207, vcc
	v_mul_f32_e32 v96, v96, v208
	v_mul_f32_e32 v97, v97, v208
	v_mul_f32_e32 v98, v98, v208
	v_mul_f32_e32 v99, v99, v208
	v_fma_f32 v96, v96, v32, v48
	v_fma_f32 v97, v97, v33, v49
	v_fma_f32 v98, v98, v34, v50
	v_fma_f32 v99, v99, v35, v51
	v_cvt_pk_bf16_f32 v96, v96, v97
	v_cvt_pk_bf16_f32 v97, v98, v99
	s_nop 0
	global_store_dwordx2 v4, v[96:97], s[30:31]
	v_mul_f32_e32 v100, v100, v208
	v_mul_f32_e32 v101, v101, v208
	v_mul_f32_e32 v102, v102, v208
	v_mul_f32_e32 v103, v103, v208
	v_fma_f32 v100, v100, v36, v52
	v_fma_f32 v101, v101, v37, v53
	v_fma_f32 v102, v102, v38, v54
	v_fma_f32 v103, v103, v39, v55
	v_cvt_pk_bf16_f32 v100, v100, v101
	v_cvt_pk_bf16_f32 v101, v102, v103
	s_nop 0
	global_store_dwordx2 v4, v[100:101], s[30:31] offset:512
	v_mul_f32_e32 v104, v104, v208
	v_mul_f32_e32 v105, v105, v208
	v_mul_f32_e32 v106, v106, v208
	v_mul_f32_e32 v107, v107, v208
	v_fma_f32 v104, v104, v40, v56
	v_fma_f32 v105, v105, v41, v57
	v_fma_f32 v106, v106, v42, v58
	v_fma_f32 v107, v107, v43, v59
	v_cvt_pk_bf16_f32 v104, v104, v105
	v_cvt_pk_bf16_f32 v105, v106, v107
	s_nop 0
	global_store_dwordx2 v4, v[104:105], s[30:31] offset:1024
	v_mul_f32_e32 v108, v108, v208
	v_mul_f32_e32 v109, v109, v208
	v_mul_f32_e32 v110, v110, v208
	v_mul_f32_e32 v111, v111, v208
	v_fma_f32 v108, v108, v44, v60
	v_fma_f32 v109, v109, v45, v61
	v_fma_f32 v110, v110, v46, v62
	v_fma_f32 v111, v111, v47, v63
	v_cvt_pk_bf16_f32 v108, v108, v109
	v_cvt_pk_bf16_f32 v109, v110, v111
	s_nop 0
	global_store_dwordx2 v4, v[108:109], s[30:31] offset:1536
